# v22 plus 64-byte alignment of the two diff-attention loop bodies (code placement)
# speedup vs baseline: 1.0021x; 1.0021x over previous
; #define LAS __attribute__((address_space(3)))
; template <bool DIFF> ...
;     ...
;     for (int t = 0; t < NT; ++t) {
;         const int buf = t & 1;
;         if (t + 1 < NT) ATT_GLOAD(t + 1);
;         if (t < nt_w) {
;             const LAS unsigned char* kb_ = lds + buf * BUFB; const LAS unsigned char* vb_ = kb_ + KTILEB;
;             f32x16 pr[2];
;             const LAS unsigned char* vbase = vb_ + (4 * hi + ((lane & 15) >> 2)) * VROWB + (sdv + ((lane >> 4) & 1) * 16 + (lane & 3) * 4) * 2;
.LBB0_337:
	s_andn2_b64 vcc, exec, s[0:1]
	s_and_b32 s0, s45, 1
	s_cbranch_vccnz .LBB0_342
	s_mul_i32 s1, s0, 0x9400
	s_add_i32 s1, s1, 0
	v_add_u32_e32 v96, s1, v215
	v_add3_u32 v97, s1, v214, v213
	v_add_u32_e32 v221, v96, v209
	.p2align	6

; #define LAS __attribute__((address_space(3)))
; template <bool DIFF> ...
;     ...
;     for (int t = 0; t < NT; ++t) {
;         const int buf = t & 1;
;         if (t + 1 < NT) ATT_GLOAD(t + 1);
;         if (t < nt_w) {
;             const LAS unsigned char* kb_ = lds + buf * BUFB; const LAS unsigned char* vb_ = kb_ + KTILEB;
;             f32x16 pr[2];
;             const LAS unsigned char* vbase = vb_ + (4 * hi + ((lane & 15) >> 2)) * VROWB + (sdv + ((lane >> 4) & 1) * 16 + (lane & 3) * 4) * 2;
.LBB0_362:
	s_andn2_b64 vcc, exec, s[0:1]
	s_and_b32 s0, s26, 1
	s_cbranch_vccnz .LBB0_367
	s_mul_i32 s1, s0, 0x9400
	s_add_i32 s1, s1, 0
	v_add_u32_e32 v96, s1, v213
	v_add3_u32 v97, s1, v215, v214
	v_add_u32_e32 v221, v96, v212
	.p2align	6
